# v40 + row-sum v_pk_add_f32 chain split into two scalar v_add_f32 chains (bit-identical)
# speedup vs baseline: 1.0028x; 1.0027x over previous
.LBB0_1608:
	v_add_f32_e32 v14, 0, v170
	v_add_f32_e32 v15, 0, v171
	v_cvt_pk_bf16_f32 v124, v170, v172
	v_add_f32_e32 v14, v172, v14
	v_add_f32_e32 v15, v173, v15
	v_cvt_pk_bf16_f32 v125, v174, v176
	v_add_f32_e32 v14, v174, v14
	v_add_f32_e32 v15, v175, v15
	v_cvt_pk_bf16_f32 v126, v178, v180
	v_add_f32_e32 v14, v176, v14
	v_add_f32_e32 v15, v177, v15
	v_cvt_pk_bf16_f32 v127, v182, v184
	v_add_f32_e32 v14, v178, v14
	v_add_f32_e32 v15, v179, v15
	v_cvt_pk_bf16_f32 v128, v186, v188
	v_add_f32_e32 v14, v180, v14
	v_add_f32_e32 v15, v181, v15
	v_cvt_pk_bf16_f32 v129, v190, v192
	v_add_f32_e32 v14, v182, v14
	v_add_f32_e32 v15, v183, v15
	v_cvt_pk_bf16_f32 v130, v194, v196
	v_add_f32_e32 v14, v184, v14
	v_add_f32_e32 v15, v185, v15
	v_cvt_pk_bf16_f32 v131, v198, v200
	v_add_f32_e32 v14, v186, v14
	v_add_f32_e32 v15, v187, v15
	v_cvt_pk_bf16_f32 v132, v171, v173
	v_add_f32_e32 v14, v188, v14
	v_add_f32_e32 v15, v189, v15
	v_cvt_pk_bf16_f32 v133, v175, v177
	v_add_f32_e32 v14, v190, v14
	v_add_f32_e32 v15, v191, v15
	v_cvt_pk_bf16_f32 v134, v179, v181
	v_add_f32_e32 v14, v192, v14
	v_add_f32_e32 v15, v193, v15
	v_cvt_pk_bf16_f32 v135, v183, v185
	v_add_f32_e32 v14, v194, v14
	v_add_f32_e32 v15, v195, v15
	v_cvt_pk_bf16_f32 v136, v187, v189
	v_add_f32_e32 v14, v196, v14
	v_add_f32_e32 v15, v197, v15
	v_cvt_pk_bf16_f32 v137, v191, v193
	v_add_f32_e32 v14, v198, v14
	v_add_f32_e32 v15, v199, v15
	v_cvt_pk_bf16_f32 v138, v195, v197
	v_add_f32_e32 v14, v200, v14
	v_add_f32_e32 v15, v201, v15
	v_cvt_pk_bf16_f32 v139, v199, v201
	v_add_f32_e32 v0, v14, v15
	s_waitcnt lgkmcnt(7)
	v_mfma_f32_32x32x16_bf16 v[96:111], v[80:83], v[144:147], 0
	v_add_u32_e32 v14, s71, v209
	s_waitcnt lgkmcnt(6)
	v_mfma_f32_32x32x16_bf16 v[80:95], v[84:87], v[144:147], 0
	s_waitcnt lgkmcnt(4)
	v_mfma_f32_32x32x16_bf16 v[80:95], v[112:115], v[148:151], v[80:95]
	v_mfma_f32_32x32x16_bf16 v[96:111], v[6:9], v[148:151], v[96:111]
	s_waitcnt lgkmcnt(2)
	v_mfma_f32_32x32x16_bf16 v[80:95], v[116:119], v[152:155], v[80:95]
	v_mfma_f32_32x32x16_bf16 v[96:111], v[10:13], v[152:155], v[96:111]
	ds_read_b128 v[6:9], v14 offset:16384
	ds_read_b128 v[10:13], v14 offset:16896
	ds_read_b128 v[112:115], v14 offset:17408
	ds_read_b128 v[116:119], v14 offset:17920
	s_waitcnt lgkmcnt(4)
	v_mfma_f32_32x32x16_bf16 v[80:95], v[120:123], v[156:159], v[80:95]
	v_mfma_f32_32x32x16_bf16 v[96:111], v[2:5], v[156:159], v[96:111]
	s_waitcnt lgkmcnt(3)
	v_mfma_f32_32x32x16_bf16 v[64:79], v[6:9], v[124:127], v[64:79]
	ds_read_b128 v[2:5], v14 offset:20480
	s_add_i32 s3, s68, 3
	s_and_b32 s69, s3, 3
	s_lshl_b32 s69, s69, 15
	s_add_i32 s72, s68, 2
	s_and_b32 s72, s72, 3
	s_lshl_b32 s72, s72, 15
	s_add_i32 s71, s68, 1
	s_and_b32 s71, s71, 3
	s_lshl_b32 s71, s71, 15
	s_add_i32 s3, s68, 1
	s_cmp_ge_u32 s3, s65
	s_cselect_b64 s[8:9], -1, 0
	v_exp_f32_e32 v170, v96
	v_exp_f32_e32 v172, v97
	s_waitcnt lgkmcnt(3)
	v_mfma_f32_32x32x16_bf16 v[48:63], v[10:13], v[124:127], v[48:63]
	ds_read_b128 v[6:9], v14 offset:20992
	v_exp_f32_e32 v174, v98
	v_exp_f32_e32 v176, v99
	s_waitcnt lgkmcnt(3)
	v_mfma_f32_32x32x16_bf16 v[32:47], v[112:115], v[124:127], v[32:47]
	ds_read_b128 v[10:13], v14 offset:21504
	v_exp_f32_e32 v178, v100
	v_exp_f32_e32 v180, v101
	s_waitcnt lgkmcnt(3)
	v_mfma_f32_32x32x16_bf16 v[16:31], v[116:119], v[124:127], v[16:31]
	ds_read_b128 v[96:99], v14 offset:22016
	v_exp_f32_e32 v182, v102
	v_exp_f32_e32 v184, v103
	s_waitcnt lgkmcnt(3)
	v_mfma_f32_32x32x16_bf16 v[64:79], v[2:5], v[128:131], v[64:79]
	ds_read_b128 v[2:5], v14 offset:24576
	v_exp_f32_e32 v186, v104
	v_exp_f32_e32 v188, v105
	s_waitcnt lgkmcnt(3)
	v_mfma_f32_32x32x16_bf16 v[48:63], v[6:9], v[128:131], v[48:63]
	ds_read_b128 v[6:9], v14 offset:25088
	v_exp_f32_e32 v190, v106
	v_exp_f32_e32 v192, v107
	s_waitcnt lgkmcnt(3)
	v_mfma_f32_32x32x16_bf16 v[32:47], v[10:13], v[128:131], v[32:47]
	ds_read_b128 v[10:13], v14 offset:25600
	v_exp_f32_e32 v194, v108
	v_exp_f32_e32 v196, v109
	s_waitcnt lgkmcnt(3)
	v_mfma_f32_32x32x16_bf16 v[16:31], v[96:99], v[128:131], v[16:31]
	ds_read_b128 v[96:99], v14 offset:26112
	v_exp_f32_e32 v198, v110
	v_exp_f32_e32 v200, v111
	s_waitcnt lgkmcnt(3)
	v_mfma_f32_32x32x16_bf16 v[64:79], v[2:5], v[132:135], v[64:79]
	ds_read_b128 v[2:5], v14 offset:28672
	v_exp_f32_e32 v171, v80
	v_exp_f32_e32 v173, v81
	s_waitcnt lgkmcnt(3)
	v_mfma_f32_32x32x16_bf16 v[48:63], v[6:9], v[132:135], v[48:63]
	ds_read_b128 v[6:9], v14 offset:29184
	v_exp_f32_e32 v175, v82
	v_exp_f32_e32 v177, v83
	s_waitcnt lgkmcnt(3)
	v_mfma_f32_32x32x16_bf16 v[32:47], v[10:13], v[132:135], v[32:47]
	ds_read_b128 v[10:13], v14 offset:29696
	v_exp_f32_e32 v179, v84
	v_exp_f32_e32 v181, v85
	s_waitcnt lgkmcnt(3)
	v_mfma_f32_32x32x16_bf16 v[16:31], v[96:99], v[132:135], v[16:31]
	ds_read_b128 v[80:83], v14 offset:30208
	v_exp_f32_e32 v183, v86
	v_exp_f32_e32 v185, v87
	s_waitcnt lgkmcnt(3)
	v_mfma_f32_32x32x16_bf16 v[64:79], v[2:5], v[136:139], v[64:79]
	v_exp_f32_e32 v187, v88
	v_exp_f32_e32 v189, v89
	s_waitcnt lgkmcnt(2)
	v_mfma_f32_32x32x16_bf16 v[48:63], v[6:9], v[136:139], v[48:63]
	v_exp_f32_e32 v191, v90
	v_exp_f32_e32 v193, v91
	s_waitcnt lgkmcnt(1)
	v_mfma_f32_32x32x16_bf16 v[32:47], v[10:13], v[136:139], v[32:47]
	v_exp_f32_e32 v195, v92
	v_exp_f32_e32 v197, v93
	s_waitcnt lgkmcnt(0)
	v_mfma_f32_32x32x16_bf16 v[16:31], v[80:83], v[136:139], v[16:31]
	v_exp_f32_e32 v199, v94
	v_exp_f32_e32 v201, v95
	v_add_f32_e32 v210, v210, v0

.Lyka_xtail:
	s_cmp_lg_u32 s59, s68
	s_cbranch_scc1 .LBB0_1610
	v_add_f32_e32 v14, 0, v170
	v_add_f32_e32 v15, 0, v171
	v_cvt_pk_bf16_f32 v124, v170, v172
	v_add_f32_e32 v14, v172, v14
	v_add_f32_e32 v15, v173, v15
	v_cvt_pk_bf16_f32 v125, v174, v176
	v_add_f32_e32 v14, v174, v14
	v_add_f32_e32 v15, v175, v15
	v_cvt_pk_bf16_f32 v126, v178, v180
	v_add_f32_e32 v14, v176, v14
	v_add_f32_e32 v15, v177, v15
	v_cvt_pk_bf16_f32 v127, v182, v184
	v_add_f32_e32 v14, v178, v14
	v_add_f32_e32 v15, v179, v15
	v_cvt_pk_bf16_f32 v128, v186, v188
	v_add_f32_e32 v14, v180, v14
	v_add_f32_e32 v15, v181, v15
	v_cvt_pk_bf16_f32 v129, v190, v192
	v_add_f32_e32 v14, v182, v14
	v_add_f32_e32 v15, v183, v15
	v_cvt_pk_bf16_f32 v130, v194, v196
	v_add_f32_e32 v14, v184, v14
	v_add_f32_e32 v15, v185, v15
	v_cvt_pk_bf16_f32 v131, v198, v200
	v_add_f32_e32 v14, v186, v14
	v_add_f32_e32 v15, v187, v15
	v_cvt_pk_bf16_f32 v132, v171, v173
	v_add_f32_e32 v14, v188, v14
	v_add_f32_e32 v15, v189, v15
	v_cvt_pk_bf16_f32 v133, v175, v177
	v_add_f32_e32 v14, v190, v14
	v_add_f32_e32 v15, v191, v15
	v_cvt_pk_bf16_f32 v134, v179, v181
	v_add_f32_e32 v14, v192, v14
	v_add_f32_e32 v15, v193, v15
	v_cvt_pk_bf16_f32 v135, v183, v185
	v_add_f32_e32 v14, v194, v14
	v_add_f32_e32 v15, v195, v15
	v_cvt_pk_bf16_f32 v136, v187, v189
	v_add_f32_e32 v14, v196, v14
	v_add_f32_e32 v15, v197, v15
	v_cvt_pk_bf16_f32 v137, v191, v193
	v_add_f32_e32 v14, v198, v14
	v_add_f32_e32 v15, v199, v15
	v_cvt_pk_bf16_f32 v138, v195, v197
	v_add_f32_e32 v14, v200, v14
	v_add_f32_e32 v15, v201, v15
	v_cvt_pk_bf16_f32 v139, v199, v201
	v_add_f32_e32 v0, v14, v15
	v_add_f32_e32 v210, v210, v0
	v_add_u32_e32 v14, s71, v209
	ds_read_b128 v[2:5], v14 offset:16384
	ds_read_b128 v[6:9], v14 offset:16896
	ds_read_b128 v[10:13], v14 offset:17408
	ds_read_b128 v[112:115], v14 offset:17920
	s_waitcnt lgkmcnt(0)
	v_mfma_f32_32x32x16_bf16 v[64:79], v[2:5], v[124:127], v[64:79]
	v_mfma_f32_32x32x16_bf16 v[48:63], v[6:9], v[124:127], v[48:63]
	v_mfma_f32_32x32x16_bf16 v[32:47], v[10:13], v[124:127], v[32:47]
	v_mfma_f32_32x32x16_bf16 v[16:31], v[112:115], v[124:127], v[16:31]
	ds_read_b128 v[2:5], v14 offset:20480
	ds_read_b128 v[6:9], v14 offset:20992
	ds_read_b128 v[10:13], v14 offset:21504
	ds_read_b128 v[112:115], v14 offset:22016
	s_waitcnt lgkmcnt(0)
	v_mfma_f32_32x32x16_bf16 v[64:79], v[2:5], v[128:131], v[64:79]
	v_mfma_f32_32x32x16_bf16 v[48:63], v[6:9], v[128:131], v[48:63]
	v_mfma_f32_32x32x16_bf16 v[32:47], v[10:13], v[128:131], v[32:47]
	v_mfma_f32_32x32x16_bf16 v[16:31], v[112:115], v[128:131], v[16:31]
	ds_read_b128 v[2:5], v14 offset:24576
	ds_read_b128 v[6:9], v14 offset:25088
	ds_read_b128 v[10:13], v14 offset:25600
	ds_read_b128 v[112:115], v14 offset:26112
	s_waitcnt lgkmcnt(0)
	v_mfma_f32_32x32x16_bf16 v[64:79], v[2:5], v[132:135], v[64:79]
	v_mfma_f32_32x32x16_bf16 v[48:63], v[6:9], v[132:135], v[48:63]
	v_mfma_f32_32x32x16_bf16 v[32:47], v[10:13], v[132:135], v[32:47]
	v_mfma_f32_32x32x16_bf16 v[16:31], v[112:115], v[132:135], v[16:31]
	ds_read_b128 v[2:5], v14 offset:28672
	ds_read_b128 v[6:9], v14 offset:29184
	ds_read_b128 v[10:13], v14 offset:29696
	ds_read_b128 v[112:115], v14 offset:30208
	s_waitcnt lgkmcnt(0)
	v_mfma_f32_32x32x16_bf16 v[64:79], v[2:5], v[136:139], v[64:79]
	v_mfma_f32_32x32x16_bf16 v[48:63], v[6:9], v[136:139], v[48:63]
	v_mfma_f32_32x32x16_bf16 v[32:47], v[10:13], v[136:139], v[32:47]
	v_mfma_f32_32x32x16_bf16 v[16:31], v[112:115], v[136:139], v[16:31]
	s_branch .LBB0_1610

.Lyka_ytop:
	s_cmp_ge_u32 s68, s59
	s_cbranch_scc1 .Lyka_ytail
	v_add_u32_e32 v0, s72, v208
	ds_read_b128 v[80:83], v0
	ds_read_b128 v[84:87], v0 offset:512
	ds_read_b128 v[6:9], v0 offset:2048
	ds_read_b128 v[112:115], v0 offset:2560
	ds_read_b128 v[10:13], v0 offset:4096
	ds_read_b128 v[116:119], v0 offset:4608
	ds_read_b128 v[2:5], v0 offset:6144
	ds_read_b128 v[120:123], v0 offset:6656
	v_add_f32_e32 v14, 0, v170
	v_add_f32_e32 v15, 0, v171
	v_cvt_pk_bf16_f32 v124, v170, v172
	v_add_f32_e32 v14, v172, v14
	v_add_f32_e32 v15, v173, v15
	v_cvt_pk_bf16_f32 v125, v174, v176
	v_add_f32_e32 v14, v174, v14
	v_add_f32_e32 v15, v175, v15
	v_cvt_pk_bf16_f32 v126, v178, v180
	v_add_f32_e32 v14, v176, v14
	v_add_f32_e32 v15, v177, v15
	v_cvt_pk_bf16_f32 v127, v182, v184
	v_add_f32_e32 v14, v178, v14
	v_add_f32_e32 v15, v179, v15
	v_cvt_pk_bf16_f32 v128, v186, v188
	v_add_f32_e32 v14, v180, v14
	v_add_f32_e32 v15, v181, v15
	v_cvt_pk_bf16_f32 v129, v190, v192
	v_add_f32_e32 v14, v182, v14
	v_add_f32_e32 v15, v183, v15
	v_cvt_pk_bf16_f32 v130, v194, v196
	v_add_f32_e32 v14, v184, v14
	v_add_f32_e32 v15, v185, v15
	v_cvt_pk_bf16_f32 v131, v198, v200
	v_add_f32_e32 v14, v186, v14
	v_add_f32_e32 v15, v187, v15
	v_cvt_pk_bf16_f32 v132, v171, v173
	v_add_f32_e32 v14, v188, v14
	v_add_f32_e32 v15, v189, v15
	v_cvt_pk_bf16_f32 v133, v175, v177
	v_add_f32_e32 v14, v190, v14
	v_add_f32_e32 v15, v191, v15
	v_cvt_pk_bf16_f32 v134, v179, v181
	v_add_f32_e32 v14, v192, v14
	v_add_f32_e32 v15, v193, v15
	v_cvt_pk_bf16_f32 v135, v183, v185
	v_add_f32_e32 v14, v194, v14
	v_add_f32_e32 v15, v195, v15
	v_cvt_pk_bf16_f32 v136, v187, v189
	v_add_f32_e32 v14, v196, v14
	v_add_f32_e32 v15, v197, v15
	v_cvt_pk_bf16_f32 v137, v191, v193
	v_add_f32_e32 v14, v198, v14
	v_add_f32_e32 v15, v199, v15
	v_cvt_pk_bf16_f32 v138, v195, v197
	v_add_f32_e32 v14, v200, v14
	v_add_f32_e32 v15, v201, v15
	v_cvt_pk_bf16_f32 v139, v199, v201
	v_add_f32_e32 v0, v14, v15
	s_waitcnt lgkmcnt(7)
	v_mfma_f32_32x32x16_bf16 v[96:111], v[80:83], v[144:147], 0
	v_add_u32_e32 v14, s71, v209
	s_waitcnt lgkmcnt(6)
	v_mfma_f32_32x32x16_bf16 v[80:95], v[84:87], v[144:147], 0
	s_waitcnt lgkmcnt(4)
	v_mfma_f32_32x32x16_bf16 v[80:95], v[112:115], v[148:151], v[80:95]
	v_mfma_f32_32x32x16_bf16 v[96:111], v[6:9], v[148:151], v[96:111]
	s_waitcnt lgkmcnt(2)
	v_mfma_f32_32x32x16_bf16 v[80:95], v[116:119], v[152:155], v[80:95]
	v_mfma_f32_32x32x16_bf16 v[96:111], v[10:13], v[152:155], v[96:111]
	ds_read_b128 v[6:9], v14 offset:16384
	ds_read_b128 v[10:13], v14 offset:16896
	ds_read_b128 v[112:115], v14 offset:17408
	ds_read_b128 v[116:119], v14 offset:17920
	s_waitcnt lgkmcnt(4)
	v_mfma_f32_32x32x16_bf16 v[80:95], v[120:123], v[156:159], v[80:95]
	v_mfma_f32_32x32x16_bf16 v[96:111], v[2:5], v[156:159], v[96:111]
	s_waitcnt vmcnt(0)
	s_barrier
	s_add_i32 s3, s68, 3
	s_cmp_lt_u32 s3, s67
	s_cbranch_scc0 .Lyka_ynodma
	s_add_i32 s3, s69, s66
	s_mov_b32 m0, s3
	v_lshl_add_u64 v[120:121], v[168:169], 0, s[28:29]
	global_load_lds_dwordx4 v[168:169], off
	s_add_i32 m0, s3, 0x2000
	s_nop 0
	global_load_lds_dwordx4 v[120:121], off
	v_lshl_add_u64 v[120:121], v[168:169], 0, s[40:41]
	s_add_i32 m0, s3, 0x4000
	s_nop 0
	global_load_lds_dwordx4 v[120:121], off
	v_lshl_add_u64 v[120:121], v[168:169], 0, s[80:81]
	s_add_i32 m0, s3, 0x6000
	s_nop 0
	global_load_lds_dwordx4 v[120:121], off

.Lyka_ytail:
	s_cmp_lg_u32 s59, s68
	s_cbranch_scc1 .Lyka_yidle
	v_add_f32_e32 v14, 0, v170
	v_add_f32_e32 v15, 0, v171
	v_cvt_pk_bf16_f32 v124, v170, v172
	v_add_f32_e32 v14, v172, v14
	v_add_f32_e32 v15, v173, v15
	v_cvt_pk_bf16_f32 v125, v174, v176
	v_add_f32_e32 v14, v174, v14
	v_add_f32_e32 v15, v175, v15
	v_cvt_pk_bf16_f32 v126, v178, v180
	v_add_f32_e32 v14, v176, v14
	v_add_f32_e32 v15, v177, v15
	v_cvt_pk_bf16_f32 v127, v182, v184
	v_add_f32_e32 v14, v178, v14
	v_add_f32_e32 v15, v179, v15
	v_cvt_pk_bf16_f32 v128, v186, v188
	v_add_f32_e32 v14, v180, v14
	v_add_f32_e32 v15, v181, v15
	v_cvt_pk_bf16_f32 v129, v190, v192
	v_add_f32_e32 v14, v182, v14
	v_add_f32_e32 v15, v183, v15
	v_cvt_pk_bf16_f32 v130, v194, v196
	v_add_f32_e32 v14, v184, v14
	v_add_f32_e32 v15, v185, v15
	v_cvt_pk_bf16_f32 v131, v198, v200
	v_add_f32_e32 v14, v186, v14
	v_add_f32_e32 v15, v187, v15
	v_cvt_pk_bf16_f32 v132, v171, v173
	v_add_f32_e32 v14, v188, v14
	v_add_f32_e32 v15, v189, v15
	v_cvt_pk_bf16_f32 v133, v175, v177
	v_add_f32_e32 v14, v190, v14
	v_add_f32_e32 v15, v191, v15
	v_cvt_pk_bf16_f32 v134, v179, v181
	v_add_f32_e32 v14, v192, v14
	v_add_f32_e32 v15, v193, v15
	v_cvt_pk_bf16_f32 v135, v183, v185
	v_add_f32_e32 v14, v194, v14
	v_add_f32_e32 v15, v195, v15
	v_cvt_pk_bf16_f32 v136, v187, v189
	v_add_f32_e32 v14, v196, v14
	v_add_f32_e32 v15, v197, v15
	v_cvt_pk_bf16_f32 v137, v191, v193
	v_add_f32_e32 v14, v198, v14
	v_add_f32_e32 v15, v199, v15
	v_cvt_pk_bf16_f32 v138, v195, v197
	v_add_f32_e32 v14, v200, v14
	v_add_f32_e32 v15, v201, v15
	v_cvt_pk_bf16_f32 v139, v199, v201
	v_add_f32_e32 v0, v14, v15
	v_add_f32_e32 v210, v210, v0
	s_waitcnt vmcnt(0)
	s_barrier
	v_add_u32_e32 v14, s71, v209
	ds_read_b128 v[2:5], v14 offset:16384
	ds_read_b128 v[6:9], v14 offset:16896
	ds_read_b128 v[10:13], v14 offset:17408
	ds_read_b128 v[112:115], v14 offset:17920
	s_waitcnt lgkmcnt(0)
	v_mfma_f32_32x32x16_bf16 v[64:79], v[2:5], v[124:127], v[64:79]
	v_mfma_f32_32x32x16_bf16 v[48:63], v[6:9], v[124:127], v[48:63]
	v_mfma_f32_32x32x16_bf16 v[32:47], v[10:13], v[124:127], v[32:47]
	v_mfma_f32_32x32x16_bf16 v[16:31], v[112:115], v[124:127], v[16:31]
	ds_read_b128 v[2:5], v14 offset:20480
	ds_read_b128 v[6:9], v14 offset:20992
	ds_read_b128 v[10:13], v14 offset:21504
	ds_read_b128 v[112:115], v14 offset:22016
	s_waitcnt lgkmcnt(0)
	v_mfma_f32_32x32x16_bf16 v[64:79], v[2:5], v[128:131], v[64:79]
	v_mfma_f32_32x32x16_bf16 v[48:63], v[6:9], v[128:131], v[48:63]
	v_mfma_f32_32x32x16_bf16 v[32:47], v[10:13], v[128:131], v[32:47]
	v_mfma_f32_32x32x16_bf16 v[16:31], v[112:115], v[128:131], v[16:31]
	ds_read_b128 v[2:5], v14 offset:24576
	ds_read_b128 v[6:9], v14 offset:25088
	ds_read_b128 v[10:13], v14 offset:25600
	ds_read_b128 v[112:115], v14 offset:26112
	s_waitcnt lgkmcnt(0)
	v_mfma_f32_32x32x16_bf16 v[64:79], v[2:5], v[132:135], v[64:79]
	v_mfma_f32_32x32x16_bf16 v[48:63], v[6:9], v[132:135], v[48:63]
	v_mfma_f32_32x32x16_bf16 v[32:47], v[10:13], v[132:135], v[32:47]
	v_mfma_f32_32x32x16_bf16 v[16:31], v[112:115], v[132:135], v[16:31]
	ds_read_b128 v[2:5], v14 offset:28672
	ds_read_b128 v[6:9], v14 offset:29184
	ds_read_b128 v[10:13], v14 offset:29696
	ds_read_b128 v[112:115], v14 offset:30208
	s_waitcnt lgkmcnt(0)
	v_mfma_f32_32x32x16_bf16 v[64:79], v[2:5], v[136:139], v[64:79]
	v_mfma_f32_32x32x16_bf16 v[48:63], v[6:9], v[136:139], v[48:63]
	v_mfma_f32_32x32x16_bf16 v[32:47], v[10:13], v[136:139], v[32:47]
	v_mfma_f32_32x32x16_bf16 v[16:31], v[112:115], v[136:139], v[16:31]
	s_branch .Lyka_ynext

.LBB0_2161:
	v_add_f32_e32 v14, 0, v168
	v_add_f32_e32 v15, 0, v169
	v_cvt_pk_bf16_f32 v124, v168, v172
	v_add_f32_e32 v14, v172, v14
	v_add_f32_e32 v15, v173, v15
	v_cvt_pk_bf16_f32 v125, v174, v176
	v_add_f32_e32 v14, v174, v14
	v_add_f32_e32 v15, v175, v15
	v_cvt_pk_bf16_f32 v126, v178, v180
	v_add_f32_e32 v14, v176, v14
	v_add_f32_e32 v15, v177, v15
	v_cvt_pk_bf16_f32 v127, v182, v184
	v_add_f32_e32 v14, v178, v14
	v_add_f32_e32 v15, v179, v15
	v_cvt_pk_bf16_f32 v128, v186, v188
	v_add_f32_e32 v14, v180, v14
	v_add_f32_e32 v15, v181, v15
	v_cvt_pk_bf16_f32 v129, v190, v192
	v_add_f32_e32 v14, v182, v14
	v_add_f32_e32 v15, v183, v15
	v_cvt_pk_bf16_f32 v130, v194, v196
	v_add_f32_e32 v14, v184, v14
	v_add_f32_e32 v15, v185, v15
	v_cvt_pk_bf16_f32 v131, v198, v200
	v_add_f32_e32 v14, v186, v14
	v_add_f32_e32 v15, v187, v15
	v_cvt_pk_bf16_f32 v132, v169, v173
	v_add_f32_e32 v14, v188, v14
	v_add_f32_e32 v15, v189, v15
	v_cvt_pk_bf16_f32 v133, v175, v177
	v_add_f32_e32 v14, v190, v14
	v_add_f32_e32 v15, v191, v15
	v_cvt_pk_bf16_f32 v134, v179, v181
	v_add_f32_e32 v14, v192, v14
	v_add_f32_e32 v15, v193, v15
	v_cvt_pk_bf16_f32 v135, v183, v185
	v_add_f32_e32 v14, v194, v14
	v_add_f32_e32 v15, v195, v15
	v_cvt_pk_bf16_f32 v136, v187, v189
	v_add_f32_e32 v14, v196, v14
	v_add_f32_e32 v15, v197, v15
	v_cvt_pk_bf16_f32 v137, v191, v193
	v_add_f32_e32 v14, v198, v14
	v_add_f32_e32 v15, v199, v15
	v_cvt_pk_bf16_f32 v138, v195, v197
	v_add_f32_e32 v14, v200, v14
	v_add_f32_e32 v15, v201, v15
	v_cvt_pk_bf16_f32 v139, v199, v201
	v_add_f32_e32 v0, v14, v15
	s_waitcnt lgkmcnt(7)
	v_mfma_f32_32x32x16_bf16 v[96:111], v[80:83], v[144:147], 0
	v_add_u32_e32 v14, s80, v209
	s_waitcnt lgkmcnt(6)
	v_mfma_f32_32x32x16_bf16 v[80:95], v[84:87], v[144:147], 0
	s_waitcnt lgkmcnt(4)
	v_mfma_f32_32x32x16_bf16 v[80:95], v[112:115], v[148:151], v[80:95]
	v_mfma_f32_32x32x16_bf16 v[96:111], v[6:9], v[148:151], v[96:111]
	s_waitcnt lgkmcnt(2)
	v_mfma_f32_32x32x16_bf16 v[80:95], v[116:119], v[152:155], v[80:95]
	v_mfma_f32_32x32x16_bf16 v[96:111], v[10:13], v[152:155], v[96:111]
	ds_read_b128 v[6:9], v14 offset:16384
	ds_read_b128 v[10:13], v14 offset:16896
	ds_read_b128 v[112:115], v14 offset:17408
	ds_read_b128 v[116:119], v14 offset:17920
	s_waitcnt lgkmcnt(4)
	v_mfma_f32_32x32x16_bf16 v[80:95], v[120:123], v[156:159], v[80:95]
	v_mfma_f32_32x32x16_bf16 v[96:111], v[2:5], v[156:159], v[96:111]
	s_waitcnt lgkmcnt(3)
	v_mfma_f32_32x32x16_bf16 v[64:79], v[6:9], v[124:127], v[64:79]
	ds_read_b128 v[2:5], v14 offset:20480
	s_add_i32 s3, s78, 3
	s_and_b32 s79, s3, 3
	s_lshl_b32 s79, s79, 15
	s_add_i32 s81, s78, 2
	s_and_b32 s81, s81, 3
	s_lshl_b32 s81, s81, 15
	s_add_i32 s80, s78, 1
	s_and_b32 s80, s80, 3
	s_lshl_b32 s80, s80, 15
	s_add_i32 s3, s78, 1
	s_cmp_ge_u32 s3, s67
	s_cselect_b64 s[8:9], -1, 0
	v_exp_f32_e32 v168, v96
	v_exp_f32_e32 v172, v97
	s_waitcnt lgkmcnt(3)
	v_mfma_f32_32x32x16_bf16 v[48:63], v[10:13], v[124:127], v[48:63]
	ds_read_b128 v[6:9], v14 offset:20992
	v_exp_f32_e32 v174, v98
	v_exp_f32_e32 v176, v99
	s_waitcnt lgkmcnt(3)
	v_mfma_f32_32x32x16_bf16 v[32:47], v[112:115], v[124:127], v[32:47]
	ds_read_b128 v[10:13], v14 offset:21504
	v_exp_f32_e32 v178, v100
	v_exp_f32_e32 v180, v101
	s_waitcnt lgkmcnt(3)
	v_mfma_f32_32x32x16_bf16 v[16:31], v[116:119], v[124:127], v[16:31]
	ds_read_b128 v[96:99], v14 offset:22016
	v_exp_f32_e32 v182, v102
	v_exp_f32_e32 v184, v103
	s_waitcnt lgkmcnt(3)
	v_mfma_f32_32x32x16_bf16 v[64:79], v[2:5], v[128:131], v[64:79]
	ds_read_b128 v[100:103], v14 offset:24576
	v_exp_f32_e32 v186, v104
	v_exp_f32_e32 v188, v105
	s_waitcnt lgkmcnt(3)
	v_mfma_f32_32x32x16_bf16 v[48:63], v[6:9], v[128:131], v[48:63]
	ds_read_b128 v[2:5], v14 offset:25088
	v_exp_f32_e32 v190, v106
	v_exp_f32_e32 v192, v107
	s_waitcnt lgkmcnt(3)
	v_mfma_f32_32x32x16_bf16 v[32:47], v[10:13], v[128:131], v[32:47]
	ds_read_b128 v[6:9], v14 offset:25600
	v_exp_f32_e32 v194, v108
	v_exp_f32_e32 v196, v109
	s_waitcnt lgkmcnt(3)
	v_mfma_f32_32x32x16_bf16 v[16:31], v[96:99], v[128:131], v[16:31]
	ds_read_b128 v[10:13], v14 offset:26112
	v_exp_f32_e32 v198, v110
	v_exp_f32_e32 v200, v111
	s_waitcnt lgkmcnt(3)
	v_mfma_f32_32x32x16_bf16 v[64:79], v[100:103], v[132:135], v[64:79]
	ds_read_b128 v[96:99], v14 offset:28672
	v_exp_f32_e32 v169, v80
	v_exp_f32_e32 v173, v81
	s_waitcnt lgkmcnt(3)
	v_mfma_f32_32x32x16_bf16 v[48:63], v[2:5], v[132:135], v[48:63]
	ds_read_b128 v[100:103], v14 offset:29184
	v_exp_f32_e32 v175, v82
	v_exp_f32_e32 v177, v83
	s_waitcnt lgkmcnt(3)
	v_mfma_f32_32x32x16_bf16 v[32:47], v[6:9], v[132:135], v[32:47]
	ds_read_b128 v[2:5], v14 offset:29696
	v_exp_f32_e32 v179, v84
	v_exp_f32_e32 v181, v85
	s_waitcnt lgkmcnt(3)
	v_mfma_f32_32x32x16_bf16 v[16:31], v[10:13], v[132:135], v[16:31]
	ds_read_b128 v[6:9], v14 offset:30208
	v_exp_f32_e32 v183, v86
	v_exp_f32_e32 v185, v87
	s_waitcnt lgkmcnt(3)
	v_mfma_f32_32x32x16_bf16 v[64:79], v[96:99], v[136:139], v[64:79]
	v_exp_f32_e32 v187, v88
	v_exp_f32_e32 v189, v89
	s_waitcnt lgkmcnt(2)
	v_mfma_f32_32x32x16_bf16 v[48:63], v[100:103], v[136:139], v[48:63]
	v_exp_f32_e32 v191, v90
	v_exp_f32_e32 v193, v91
	s_waitcnt lgkmcnt(1)
	v_mfma_f32_32x32x16_bf16 v[32:47], v[2:5], v[136:139], v[32:47]
	v_exp_f32_e32 v195, v92
	v_exp_f32_e32 v197, v93
	s_waitcnt lgkmcnt(0)
	v_mfma_f32_32x32x16_bf16 v[16:31], v[6:9], v[136:139], v[16:31]
	v_exp_f32_e32 v199, v94
	v_exp_f32_e32 v201, v95
	v_add_f32_e32 v210, v210, v0

.Lykb_xtail:
	s_cmp_lg_u32 s66, s78
	s_cbranch_scc1 .LBB0_2163
	v_add_f32_e32 v14, 0, v168
	v_add_f32_e32 v15, 0, v169
	v_cvt_pk_bf16_f32 v124, v168, v172
	v_add_f32_e32 v14, v172, v14
	v_add_f32_e32 v15, v173, v15
	v_cvt_pk_bf16_f32 v125, v174, v176
	v_add_f32_e32 v14, v174, v14
	v_add_f32_e32 v15, v175, v15
	v_cvt_pk_bf16_f32 v126, v178, v180
	v_add_f32_e32 v14, v176, v14
	v_add_f32_e32 v15, v177, v15
	v_cvt_pk_bf16_f32 v127, v182, v184
	v_add_f32_e32 v14, v178, v14
	v_add_f32_e32 v15, v179, v15
	v_cvt_pk_bf16_f32 v128, v186, v188
	v_add_f32_e32 v14, v180, v14
	v_add_f32_e32 v15, v181, v15
	v_cvt_pk_bf16_f32 v129, v190, v192
	v_add_f32_e32 v14, v182, v14
	v_add_f32_e32 v15, v183, v15
	v_cvt_pk_bf16_f32 v130, v194, v196
	v_add_f32_e32 v14, v184, v14
	v_add_f32_e32 v15, v185, v15
	v_cvt_pk_bf16_f32 v131, v198, v200
	v_add_f32_e32 v14, v186, v14
	v_add_f32_e32 v15, v187, v15
	v_cvt_pk_bf16_f32 v132, v169, v173
	v_add_f32_e32 v14, v188, v14
	v_add_f32_e32 v15, v189, v15
	v_cvt_pk_bf16_f32 v133, v175, v177
	v_add_f32_e32 v14, v190, v14
	v_add_f32_e32 v15, v191, v15
	v_cvt_pk_bf16_f32 v134, v179, v181
	v_add_f32_e32 v14, v192, v14
	v_add_f32_e32 v15, v193, v15
	v_cvt_pk_bf16_f32 v135, v183, v185
	v_add_f32_e32 v14, v194, v14
	v_add_f32_e32 v15, v195, v15
	v_cvt_pk_bf16_f32 v136, v187, v189
	v_add_f32_e32 v14, v196, v14
	v_add_f32_e32 v15, v197, v15
	v_cvt_pk_bf16_f32 v137, v191, v193
	v_add_f32_e32 v14, v198, v14
	v_add_f32_e32 v15, v199, v15
	v_cvt_pk_bf16_f32 v138, v195, v197
	v_add_f32_e32 v14, v200, v14
	v_add_f32_e32 v15, v201, v15
	v_cvt_pk_bf16_f32 v139, v199, v201
	v_add_f32_e32 v0, v14, v15
	v_add_f32_e32 v210, v210, v0
	v_add_u32_e32 v14, s80, v209
	ds_read_b128 v[2:5], v14 offset:16384
	ds_read_b128 v[6:9], v14 offset:16896
	ds_read_b128 v[10:13], v14 offset:17408
	ds_read_b128 v[112:115], v14 offset:17920
	s_waitcnt lgkmcnt(0)
	v_mfma_f32_32x32x16_bf16 v[64:79], v[2:5], v[124:127], v[64:79]
	v_mfma_f32_32x32x16_bf16 v[48:63], v[6:9], v[124:127], v[48:63]
	v_mfma_f32_32x32x16_bf16 v[32:47], v[10:13], v[124:127], v[32:47]
	v_mfma_f32_32x32x16_bf16 v[16:31], v[112:115], v[124:127], v[16:31]
	ds_read_b128 v[2:5], v14 offset:20480
	ds_read_b128 v[6:9], v14 offset:20992
	ds_read_b128 v[10:13], v14 offset:21504
	ds_read_b128 v[112:115], v14 offset:22016
	s_waitcnt lgkmcnt(0)
	v_mfma_f32_32x32x16_bf16 v[64:79], v[2:5], v[128:131], v[64:79]
	v_mfma_f32_32x32x16_bf16 v[48:63], v[6:9], v[128:131], v[48:63]
	v_mfma_f32_32x32x16_bf16 v[32:47], v[10:13], v[128:131], v[32:47]
	v_mfma_f32_32x32x16_bf16 v[16:31], v[112:115], v[128:131], v[16:31]
	ds_read_b128 v[2:5], v14 offset:24576
	ds_read_b128 v[6:9], v14 offset:25088
	ds_read_b128 v[10:13], v14 offset:25600
	ds_read_b128 v[112:115], v14 offset:26112
	s_waitcnt lgkmcnt(0)
	v_mfma_f32_32x32x16_bf16 v[64:79], v[2:5], v[132:135], v[64:79]
	v_mfma_f32_32x32x16_bf16 v[48:63], v[6:9], v[132:135], v[48:63]
	v_mfma_f32_32x32x16_bf16 v[32:47], v[10:13], v[132:135], v[32:47]
	v_mfma_f32_32x32x16_bf16 v[16:31], v[112:115], v[132:135], v[16:31]
	ds_read_b128 v[2:5], v14 offset:28672
	ds_read_b128 v[6:9], v14 offset:29184
	ds_read_b128 v[10:13], v14 offset:29696
	ds_read_b128 v[112:115], v14 offset:30208
	s_waitcnt lgkmcnt(0)
	v_mfma_f32_32x32x16_bf16 v[64:79], v[2:5], v[136:139], v[64:79]
	v_mfma_f32_32x32x16_bf16 v[48:63], v[6:9], v[136:139], v[48:63]
	v_mfma_f32_32x32x16_bf16 v[32:47], v[10:13], v[136:139], v[32:47]
	v_mfma_f32_32x32x16_bf16 v[16:31], v[112:115], v[136:139], v[16:31]
	s_branch .LBB0_2163

.Lykb_ytop:
	s_cmp_ge_u32 s78, s66
	s_cbranch_scc1 .Lykb_ytail
	v_add_u32_e32 v0, s81, v208
	ds_read_b128 v[80:83], v0
	ds_read_b128 v[84:87], v0 offset:512
	ds_read_b128 v[6:9], v0 offset:2048
	ds_read_b128 v[112:115], v0 offset:2560
	ds_read_b128 v[10:13], v0 offset:4096
	ds_read_b128 v[116:119], v0 offset:4608
	ds_read_b128 v[2:5], v0 offset:6144
	ds_read_b128 v[120:123], v0 offset:6656
	v_add_f32_e32 v14, 0, v168
	v_add_f32_e32 v15, 0, v169
	v_cvt_pk_bf16_f32 v124, v168, v172
	v_add_f32_e32 v14, v172, v14
	v_add_f32_e32 v15, v173, v15
	v_cvt_pk_bf16_f32 v125, v174, v176
	v_add_f32_e32 v14, v174, v14
	v_add_f32_e32 v15, v175, v15
	v_cvt_pk_bf16_f32 v126, v178, v180
	v_add_f32_e32 v14, v176, v14
	v_add_f32_e32 v15, v177, v15
	v_cvt_pk_bf16_f32 v127, v182, v184
	v_add_f32_e32 v14, v178, v14
	v_add_f32_e32 v15, v179, v15
	v_cvt_pk_bf16_f32 v128, v186, v188
	v_add_f32_e32 v14, v180, v14
	v_add_f32_e32 v15, v181, v15
	v_cvt_pk_bf16_f32 v129, v190, v192
	v_add_f32_e32 v14, v182, v14
	v_add_f32_e32 v15, v183, v15
	v_cvt_pk_bf16_f32 v130, v194, v196
	v_add_f32_e32 v14, v184, v14
	v_add_f32_e32 v15, v185, v15
	v_cvt_pk_bf16_f32 v131, v198, v200
	v_add_f32_e32 v14, v186, v14
	v_add_f32_e32 v15, v187, v15
	v_cvt_pk_bf16_f32 v132, v169, v173
	v_add_f32_e32 v14, v188, v14
	v_add_f32_e32 v15, v189, v15
	v_cvt_pk_bf16_f32 v133, v175, v177
	v_add_f32_e32 v14, v190, v14
	v_add_f32_e32 v15, v191, v15
	v_cvt_pk_bf16_f32 v134, v179, v181
	v_add_f32_e32 v14, v192, v14
	v_add_f32_e32 v15, v193, v15
	v_cvt_pk_bf16_f32 v135, v183, v185
	v_add_f32_e32 v14, v194, v14
	v_add_f32_e32 v15, v195, v15
	v_cvt_pk_bf16_f32 v136, v187, v189
	v_add_f32_e32 v14, v196, v14
	v_add_f32_e32 v15, v197, v15
	v_cvt_pk_bf16_f32 v137, v191, v193
	v_add_f32_e32 v14, v198, v14
	v_add_f32_e32 v15, v199, v15
	v_cvt_pk_bf16_f32 v138, v195, v197
	v_add_f32_e32 v14, v200, v14
	v_add_f32_e32 v15, v201, v15
	v_cvt_pk_bf16_f32 v139, v199, v201
	v_add_f32_e32 v0, v14, v15
	s_waitcnt lgkmcnt(7)
	v_mfma_f32_32x32x16_bf16 v[96:111], v[80:83], v[144:147], 0
	v_add_u32_e32 v14, s80, v209
	s_waitcnt lgkmcnt(6)
	v_mfma_f32_32x32x16_bf16 v[80:95], v[84:87], v[144:147], 0
	s_waitcnt lgkmcnt(4)
	v_mfma_f32_32x32x16_bf16 v[80:95], v[112:115], v[148:151], v[80:95]
	v_mfma_f32_32x32x16_bf16 v[96:111], v[6:9], v[148:151], v[96:111]
	s_waitcnt lgkmcnt(2)
	v_mfma_f32_32x32x16_bf16 v[80:95], v[116:119], v[152:155], v[80:95]
	v_mfma_f32_32x32x16_bf16 v[96:111], v[10:13], v[152:155], v[96:111]
	ds_read_b128 v[6:9], v14 offset:16384
	ds_read_b128 v[10:13], v14 offset:16896
	ds_read_b128 v[112:115], v14 offset:17408
	ds_read_b128 v[116:119], v14 offset:17920
	s_waitcnt lgkmcnt(4)
	v_mfma_f32_32x32x16_bf16 v[80:95], v[120:123], v[156:159], v[80:95]
	v_mfma_f32_32x32x16_bf16 v[96:111], v[2:5], v[156:159], v[96:111]
	s_waitcnt vmcnt(0)
	s_barrier
	s_add_i32 s3, s78, 3
	s_cmp_lt_u32 s3, s69
	s_cbranch_scc0 .Lykb_ynodma
	s_add_i32 s3, s79, s68
	s_mov_b32 m0, s3
	v_lshl_add_u64 v[120:121], v[170:171], 0, s[24:25]
	global_load_lds_dwordx4 v[170:171], off
	s_add_i32 m0, s3, 0x2000
	s_nop 0
	global_load_lds_dwordx4 v[120:121], off
	v_lshl_add_u64 v[120:121], v[170:171], 0, s[26:27]
	s_add_i32 m0, s3, 0x4000
	s_nop 0
	global_load_lds_dwordx4 v[120:121], off
	v_lshl_add_u64 v[120:121], v[170:171], 0, s[44:45]
	s_add_i32 m0, s3, 0x6000
	s_nop 0
	global_load_lds_dwordx4 v[120:121], off

.Lykb_ytail:
	s_cmp_lg_u32 s66, s78
	s_cbranch_scc1 .Lykb_yidle
	v_add_f32_e32 v14, 0, v168
	v_add_f32_e32 v15, 0, v169
	v_cvt_pk_bf16_f32 v124, v168, v172
	v_add_f32_e32 v14, v172, v14
	v_add_f32_e32 v15, v173, v15
	v_cvt_pk_bf16_f32 v125, v174, v176
	v_add_f32_e32 v14, v174, v14
	v_add_f32_e32 v15, v175, v15
	v_cvt_pk_bf16_f32 v126, v178, v180
	v_add_f32_e32 v14, v176, v14
	v_add_f32_e32 v15, v177, v15
	v_cvt_pk_bf16_f32 v127, v182, v184
	v_add_f32_e32 v14, v178, v14
	v_add_f32_e32 v15, v179, v15
	v_cvt_pk_bf16_f32 v128, v186, v188
	v_add_f32_e32 v14, v180, v14
	v_add_f32_e32 v15, v181, v15
	v_cvt_pk_bf16_f32 v129, v190, v192
	v_add_f32_e32 v14, v182, v14
	v_add_f32_e32 v15, v183, v15
	v_cvt_pk_bf16_f32 v130, v194, v196
	v_add_f32_e32 v14, v184, v14
	v_add_f32_e32 v15, v185, v15
	v_cvt_pk_bf16_f32 v131, v198, v200
	v_add_f32_e32 v14, v186, v14
	v_add_f32_e32 v15, v187, v15
	v_cvt_pk_bf16_f32 v132, v169, v173
	v_add_f32_e32 v14, v188, v14
	v_add_f32_e32 v15, v189, v15
	v_cvt_pk_bf16_f32 v133, v175, v177
	v_add_f32_e32 v14, v190, v14
	v_add_f32_e32 v15, v191, v15
	v_cvt_pk_bf16_f32 v134, v179, v181
	v_add_f32_e32 v14, v192, v14
	v_add_f32_e32 v15, v193, v15
	v_cvt_pk_bf16_f32 v135, v183, v185
	v_add_f32_e32 v14, v194, v14
	v_add_f32_e32 v15, v195, v15
	v_cvt_pk_bf16_f32 v136, v187, v189
	v_add_f32_e32 v14, v196, v14
	v_add_f32_e32 v15, v197, v15
	v_cvt_pk_bf16_f32 v137, v191, v193
	v_add_f32_e32 v14, v198, v14
	v_add_f32_e32 v15, v199, v15
	v_cvt_pk_bf16_f32 v138, v195, v197
	v_add_f32_e32 v14, v200, v14
	v_add_f32_e32 v15, v201, v15
	v_cvt_pk_bf16_f32 v139, v199, v201
	v_add_f32_e32 v0, v14, v15
	v_add_f32_e32 v210, v210, v0
	s_waitcnt vmcnt(0)
	s_barrier
	v_add_u32_e32 v14, s80, v209
	ds_read_b128 v[2:5], v14 offset:16384
	ds_read_b128 v[6:9], v14 offset:16896
	ds_read_b128 v[10:13], v14 offset:17408
	ds_read_b128 v[112:115], v14 offset:17920
	s_waitcnt lgkmcnt(0)
	v_mfma_f32_32x32x16_bf16 v[64:79], v[2:5], v[124:127], v[64:79]
	v_mfma_f32_32x32x16_bf16 v[48:63], v[6:9], v[124:127], v[48:63]
	v_mfma_f32_32x32x16_bf16 v[32:47], v[10:13], v[124:127], v[32:47]
	v_mfma_f32_32x32x16_bf16 v[16:31], v[112:115], v[124:127], v[16:31]
	ds_read_b128 v[2:5], v14 offset:20480
	ds_read_b128 v[6:9], v14 offset:20992
	ds_read_b128 v[10:13], v14 offset:21504
	ds_read_b128 v[112:115], v14 offset:22016
	s_waitcnt lgkmcnt(0)
	v_mfma_f32_32x32x16_bf16 v[64:79], v[2:5], v[128:131], v[64:79]
	v_mfma_f32_32x32x16_bf16 v[48:63], v[6:9], v[128:131], v[48:63]
	v_mfma_f32_32x32x16_bf16 v[32:47], v[10:13], v[128:131], v[32:47]
	v_mfma_f32_32x32x16_bf16 v[16:31], v[112:115], v[128:131], v[16:31]
	ds_read_b128 v[2:5], v14 offset:24576
	ds_read_b128 v[6:9], v14 offset:25088
	ds_read_b128 v[10:13], v14 offset:25600
	ds_read_b128 v[112:115], v14 offset:26112
	s_waitcnt lgkmcnt(0)
	v_mfma_f32_32x32x16_bf16 v[64:79], v[2:5], v[132:135], v[64:79]
	v_mfma_f32_32x32x16_bf16 v[48:63], v[6:9], v[132:135], v[48:63]
	v_mfma_f32_32x32x16_bf16 v[32:47], v[10:13], v[132:135], v[32:47]
	v_mfma_f32_32x32x16_bf16 v[16:31], v[112:115], v[132:135], v[16:31]
	ds_read_b128 v[2:5], v14 offset:28672
	ds_read_b128 v[6:9], v14 offset:29184
	ds_read_b128 v[10:13], v14 offset:29696
	ds_read_b128 v[112:115], v14 offset:30208
	s_waitcnt lgkmcnt(0)
	v_mfma_f32_32x32x16_bf16 v[64:79], v[2:5], v[136:139], v[64:79]
	v_mfma_f32_32x32x16_bf16 v[48:63], v[6:9], v[136:139], v[48:63]
	v_mfma_f32_32x32x16_bf16 v[32:47], v[10:13], v[136:139], v[32:47]
	v_mfma_f32_32x32x16_bf16 v[16:31], v[112:115], v[136:139], v[16:31]
	s_branch .Lykb_ynext
